# grid barrier: the first workgroup of an XCD to arrive starts the L2 write-back asynchronously (on top of the early L1 invalidate)
# speedup vs baseline: 1.0058x; 1.0058x over previous
; __device__ __forceinline__ unsigned xb_add(unsigned* p, unsigned v) { return __hip_atomic_fetch_add(p, v, __ATOMIC_RELAXED, __HIP_MEMORY_SCOPE_AGENT); }
; __device__ __forceinline__ void xcd_barrier(const XcdBarrier& b) {
;     ...
;         const unsigned old = xb_add(&bar[XB_XSUB(b.x)], 1u);
;         const unsigned gen = old / nloc;
;         if (old + 1u == (gen + 1u) * nloc) {
.LBB0_111:
	s_or_b64 exec, exec, s[10:11]
	v_cvt_f32_u32_e32 v4, v2
	s_waitcnt vmcnt(0)
	v_readfirstlane_b32 s8, v3
	v_sub_u32_e32 v3, 0, v2
	v_rcp_iflag_f32_e32 v4, v4
	v_add_u32_e32 v5, s8, v1
	v_mul_f32_e32 v4, 0x4f7ffffe, v4
	v_cvt_u32_f32_e32 v4, v4
	v_mul_lo_u32 v1, v3, v4
	v_mul_hi_u32 v1, v4, v1
	v_add_u32_e32 v1, v4, v1
	v_mul_hi_u32 v1, v5, v1
	v_mul_lo_u32 v3, v1, v2
	v_sub_u32_e32 v3, v5, v3
	v_add_u32_e32 v4, 1, v1
	v_cmp_ge_u32_e32 vcc, v3, v2
	s_nop 1
	v_cndmask_b32_e32 v1, v1, v4, vcc
	v_sub_u32_e32 v4, v3, v2
	v_cndmask_b32_e32 v3, v3, v4, vcc
	v_add_u32_e32 v4, 1, v1
	v_cmp_ge_u32_e32 vcc, v3, v2
	v_add_u32_e32 v3, 1, v5
	s_nop 0
	v_cndmask_b32_e32 v1, v1, v4, vcc
	v_mul_lo_u32 v4, v2, v1
	v_add_u32_e32 v2, v4, v2
	v_cmp_eq_u32_e32 vcc, v5, v4
	s_and_saveexec_b64 s[10:11], vcc
	s_cbranch_execz .Lewb_0
	buffer_wbl2 sc1
.Lewb_0:
	s_or_b64 exec, exec, s[10:11]
	v_cmp_ne_u32_e32 vcc, v3, v2
	s_and_saveexec_b64 s[8:9], vcc
	s_xor_b64 s[8:9], exec, s[8:9]
	s_cbranch_execz .LBB0_125
	s_waitcnt lgkmcnt(0)
	v_mov_b32_e32 v0, 0x2000
	global_load_dword v0, v0, s[6:7] offset:1024 sc1
	s_add_u32 s14, s6, 0x2400
	s_addc_u32 s15, s7, 0
	s_waitcnt vmcnt(0)
	v_cmp_eq_u32_e32 vcc, v0, v1
	s_and_saveexec_b64 s[10:11], vcc
	s_cbranch_execz .LBB0_124
	s_add_u32 s12, s88, 0x80200
	s_addc_u32 s13, s89, 0
	s_mov_b32 s18, 1
	s_mov_b64 s[16:17], 0
	v_mov_b32_e32 v0, 0
	s_branch .LBB0_115

; __device__ __forceinline__ unsigned xb_add(unsigned* p, unsigned v) { return __hip_atomic_fetch_add(p, v, __ATOMIC_RELAXED, __HIP_MEMORY_SCOPE_AGENT); }
; __device__ __forceinline__ void xcd_barrier(const XcdBarrier& b) {
;     ...
;         const unsigned old = xb_add(&bar[XB_XSUB(b.x)], 1u);
;         const unsigned gen = old / nloc;
;         if (old + 1u == (gen + 1u) * nloc) {
.LBB0_190:
	s_or_b64 exec, exec, s[8:9]
	v_cvt_f32_u32_e32 v4, v2
	s_waitcnt vmcnt(0)
	v_readfirstlane_b32 s6, v3
	v_sub_u32_e32 v3, 0, v2
	v_rcp_iflag_f32_e32 v4, v4
	v_add_u32_e32 v5, s6, v1
	v_mul_f32_e32 v4, 0x4f7ffffe, v4
	v_cvt_u32_f32_e32 v4, v4
	v_mul_lo_u32 v1, v3, v4
	v_mul_hi_u32 v1, v4, v1
	v_add_u32_e32 v1, v4, v1
	v_mul_hi_u32 v1, v5, v1
	v_mul_lo_u32 v3, v1, v2
	v_sub_u32_e32 v3, v5, v3
	v_add_u32_e32 v4, 1, v1
	v_cmp_ge_u32_e32 vcc, v3, v2
	s_nop 1
	v_cndmask_b32_e32 v1, v1, v4, vcc
	v_sub_u32_e32 v4, v3, v2
	v_cndmask_b32_e32 v3, v3, v4, vcc
	v_add_u32_e32 v4, 1, v1
	v_cmp_ge_u32_e32 vcc, v3, v2
	v_add_u32_e32 v3, 1, v5
	s_nop 0
	v_cndmask_b32_e32 v1, v1, v4, vcc
	v_mul_lo_u32 v4, v2, v1
	v_add_u32_e32 v2, v4, v2
	v_cmp_eq_u32_e32 vcc, v5, v4
	s_and_saveexec_b64 s[8:9], vcc
	s_cbranch_execz .Lewb_1
	buffer_wbl2 sc1
.Lewb_1:
	s_or_b64 exec, exec, s[8:9]
	v_cmp_ne_u32_e32 vcc, v3, v2
	s_and_saveexec_b64 s[6:7], vcc
	s_xor_b64 s[6:7], exec, s[6:7]
	s_cbranch_execz .LBB0_204
	s_waitcnt lgkmcnt(0)
	v_mov_b32_e32 v0, 0x2000
	global_load_dword v0, v0, s[4:5] offset:1024 sc1
	s_add_u32 s12, s4, 0x2400
	s_addc_u32 s13, s5, 0
	s_waitcnt vmcnt(0)
	v_cmp_eq_u32_e32 vcc, v0, v1
	s_and_saveexec_b64 s[8:9], vcc
	s_cbranch_execz .LBB0_203
	s_add_u32 s10, s88, 0x80200
	s_addc_u32 s11, s89, 0
	s_mov_b32 s18, 1
	s_mov_b64 s[14:15], 0
	v_mov_b32_e32 v0, 0
	s_branch .LBB0_194

; __device__ __forceinline__ unsigned xb_ld(unsigned* p)              { return __hip_atomic_load(p, __ATOMIC_RELAXED, __HIP_MEMORY_SCOPE_AGENT); }
; __device__ __forceinline__ unsigned xb_add(unsigned* p, unsigned v) { return __hip_atomic_fetch_add(p, v, __ATOMIC_RELAXED, __HIP_MEMORY_SCOPE_AGENT); }
; #define XB_SPIN(cond, bar) do { unsigned _sp = 0; while (cond) { __builtin_amdgcn_s_sleep(1); \
;     if ((++_sp & 255u) == 0u) { if (xb_ld(&(bar)[XB_TMO])) break; if (_sp > XB_SPIN_CAP) { atomicAdd(&(bar)[XB_TMO], 1u); break; } } } } while (0)
; __device__ __forceinline__ void xcd_barrier(const XcdBarrier& b) {
;     ...
;         if (old + 1u == (gen + 1u) * nloc) {
;             __builtin_amdgcn_fence(__ATOMIC_RELEASE, "agent");
;             asm volatile("s_waitcnt vmcnt(0)" ::: "memory");
;             const unsigned og = xb_add(&bar[XB_TOP], 1u);
;             const unsigned tg = og / nx;
;             if (og + 1u == (tg + 1u) * nx) xb_add(&bar[XB_TOPGEN], 1u);
;             else XB_SPIN(xb_ld(&bar[XB_TOPGEN]) == tg, bar);
;             __builtin_amdgcn_fence(__ATOMIC_ACQUIRE, "agent");
;             xb_add(&bar[XB_XGEN(b.x)], 1u);
;             asm volatile("s_waitcnt vmcnt(0)" ::: "memory");
;         } else {
;             XB_SPIN(xb_ld(&bar[XB_XGEN(b.x)]) == gen, bar);
.Lewb_8:
	s_or_b64 exec, exec, s[8:9]
	v_cmp_ne_u32_e32 vcc, v3, v2
	s_and_saveexec_b64 s[6:7], vcc
	s_xor_b64 s[6:7], exec, s[6:7]
	s_cbranch_execz .LBB0_1334
	s_waitcnt lgkmcnt(0)
	v_mov_b32_e32 v0, 0x2000
	global_load_dword v0, v0, s[4:5] offset:1024 sc1
	s_add_u32 s12, s4, 0x2400
	s_addc_u32 s13, s5, 0
	s_waitcnt vmcnt(0)
	v_cmp_eq_u32_e32 vcc, v0, v1
	s_and_saveexec_b64 s[8:9], vcc
	s_cbranch_execz .LBB0_1333
	s_add_u32 s10, s88, 0x80200
	s_addc_u32 s11, s89, 0
	s_mov_b32 s24, 1
	s_mov_b64 s[14:15], 0
	v_mov_b32_e32 v0, 0
	s_branch .LBB0_1324
